# MLA unit_fixed tile loop: first six K-fragment ds_reads hoisted above half-0 LDS-DMA issue block (DMA temps renamed to v230:231)
# baseline (speedup 1.0000x reference)
.LBB0_862:
	s_bitcmp1_b32 s53, 0
	s_cselect_b32 s55, 0x6400, 0
	s_and_b32 s97, s96, 0x4000
	v_add_u32_e32 v205, s55, v201
	ds_read_b128 v[82:85], v205
	ds_read_b128 v[206:209], v205 offset:32
	ds_read_b128 v[210:213], v205 offset:12800
	ds_read_b128 v[218:221], v205 offset:64
	ds_read_b128 v[222:225], v205 offset:12832
	ds_read_b128 v[226:229], v205 offset:12864
	v_add_u32_e32 v214, s97, v204
	v_add_u32_e32 v215, 0xc800, v214
	s_and_b64 vcc, exec, s[6:7]
	s_cbranch_vccnz .LBB0_867
	s_cmp_eq_u32 s8, 0x2f40000
	s_cbranch_scc1 .LBB0_866
	s_add_u32 s0, s74, s8
	s_addc_u32 s1, s33, s9
	s_add_u32 s0, s0, 0x35fc0000
	s_addc_u32 s1, s1, 0
	s_sub_i32 s62, 0, s55
	s_add_i32 s63, s62, 0x6400
	s_add_i32 vcc_lo, s63, s54
	v_lshl_add_u64 v[230:231], v[182:183], 1, s[0:1]
	s_mov_b32 vcc_hi, m0
	s_mov_b32 m0, vcc_lo
	s_nop 0
	global_load_lds_dwordx4 v[230:231], off
	s_mov_b32 m0, vcc_hi
	s_add_i32 vcc_lo, s63, s71
	v_lshl_add_u64 v[230:231], v[184:185], 1, s[0:1]
	s_mov_b32 vcc_hi, m0
	s_mov_b32 m0, vcc_lo
	s_nop 0
	global_load_lds_dwordx4 v[230:231], off
	s_mov_b32 m0, vcc_hi
	v_lshl_add_u64 v[230:231], v[186:187], 1, s[0:1]
	s_add_i32 s63, s63, s70
	s_mov_b32 s66, m0
	s_mov_b32 m0, s63
	s_nop 0
	global_load_lds_dwordx4 v[230:231], off
	s_mov_b32 m0, s66
	s_and_b64 vcc, exec, s[2:3]
	s_cbranch_vccnz .LBB0_866
	s_add_i32 s62, s62, 0xc400
	v_lshl_add_u64 v[230:231], v[188:189], 1, s[0:1]
	s_mov_b32 s0, m0
	s_mov_b32 m0, s62
	s_nop 0
	global_load_lds_dwordx4 v[230:231], off
	s_mov_b32 m0, s0
.LBB0_866:
	s_sub_i32 s0, 0, s97
	s_add_i32 s0, s0, 0x10800
	v_lshl_add_u64 v[230:231], v[190:191], 1, s[76:77]
	s_add_i32 s1, s0, s54
	s_mov_b32 s62, m0
	s_mov_b32 m0, s1
	s_nop 0
	global_load_lds_dwordx4 v[230:231], off
	s_mov_b32 m0, s62
	v_lshl_add_u64 v[230:231], v[192:193], 1, s[76:77]
	s_add_i32 s0, s0, s71
	s_mov_b32 s1, m0
	s_mov_b32 m0, s0
	s_nop 0
	global_load_lds_dwordx4 v[230:231], off
	s_mov_b32 m0, s1
.LBB0_867:
	s_waitcnt lgkmcnt(5)
	v_mfma_f32_32x32x16_bf16 v[98:113], v[82:85], v[114:117], v[66:81]
	s_waitcnt lgkmcnt(3)
	v_mfma_f32_32x32x16_bf16 v[82:97], v[210:213], v[114:117], v[66:81]
	ds_read_b128 v[210:213], v205 offset:96
	ds_read_b128 v[230:233], v205 offset:12896
	v_mfma_f32_32x32x16_bf16 v[98:113], v[206:209], v[118:121], v[98:113]
	s_waitcnt lgkmcnt(3)
	v_mfma_f32_32x32x16_bf16 v[82:97], v[222:225], v[118:121], v[82:97]
	ds_read_b128 v[206:209], v205 offset:128
	ds_read_b128 v[222:225], v205 offset:12928
	v_mfma_f32_32x32x16_bf16 v[98:113], v[218:221], v[122:125], v[98:113]
	s_waitcnt lgkmcnt(4)
	v_mfma_f32_32x32x16_bf16 v[82:97], v[226:229], v[122:125], v[82:97]
	ds_read_b128 v[218:221], v205 offset:160
	ds_read_b128 v[226:229], v205 offset:12960
	s_waitcnt lgkmcnt(5)
	v_mfma_f32_32x32x16_bf16 v[98:113], v[210:213], v[126:129], v[98:113]
	s_waitcnt lgkmcnt(4)
	v_mfma_f32_32x32x16_bf16 v[82:97], v[230:233], v[126:129], v[82:97]
	ds_read_b128 v[210:213], v205 offset:192
	ds_read_b128 v[230:233], v205 offset:12992
	s_waitcnt lgkmcnt(5)
	v_mfma_f32_32x32x16_bf16 v[98:113], v[206:209], v[130:133], v[98:113]
	s_waitcnt lgkmcnt(4)
	v_mfma_f32_32x32x16_bf16 v[82:97], v[222:225], v[130:133], v[82:97]
	ds_read_b128 v[206:209], v205 offset:224
	ds_read_b128 v[222:225], v205 offset:13024
	s_waitcnt lgkmcnt(5)
	v_mfma_f32_32x32x16_bf16 v[98:113], v[218:221], v[134:137], v[98:113]
	s_waitcnt lgkmcnt(4)
	v_mfma_f32_32x32x16_bf16 v[82:97], v[226:229], v[134:137], v[82:97]
	ds_read_b128 v[218:221], v205 offset:256
	ds_read_b128 v[226:229], v205 offset:13056
	s_waitcnt lgkmcnt(5)
	v_mfma_f32_32x32x16_bf16 v[98:113], v[210:213], v[138:141], v[98:113]
	s_waitcnt lgkmcnt(4)
	v_mfma_f32_32x32x16_bf16 v[82:97], v[230:233], v[138:141], v[82:97]
	ds_read_b128 v[210:213], v205 offset:288
	ds_read_b128 v[230:233], v205 offset:13088
	ds_read_b64_tr_b16 v[234:235], v214 offset:51200
	ds_read_b64_tr_b16 v[236:237], v214 offset:53248
	s_waitcnt lgkmcnt(7)
	v_mfma_f32_32x32x16_bf16 v[98:113], v[206:209], v[142:145], v[98:113]
	s_waitcnt lgkmcnt(6)
	v_mfma_f32_32x32x16_bf16 v[82:97], v[222:225], v[142:145], v[82:97]
	ds_read_b128 v[206:209], v205 offset:320
	ds_read_b128 v[222:225], v205 offset:13120
	ds_read_b64_tr_b16 v[238:239], v214 offset:55296
	ds_read_b64_tr_b16 v[240:241], v214 offset:57344
	s_waitcnt lgkmcnt(9)
	v_mfma_f32_32x32x16_bf16 v[98:113], v[218:221], v[146:149], v[98:113]
	s_waitcnt lgkmcnt(8)
	v_mfma_f32_32x32x16_bf16 v[82:97], v[226:229], v[146:149], v[82:97]
	ds_read_b128 v[218:221], v205 offset:352
	ds_read_b128 v[226:229], v205 offset:13152
	ds_read_b64_tr_b16 v[242:243], v214 offset:59392
	ds_read_b64_tr_b16 v[244:245], v214 offset:61440
	s_waitcnt lgkmcnt(11)
	v_mfma_f32_32x32x16_bf16 v[98:113], v[210:213], v[154:157], v[98:113]
	s_waitcnt lgkmcnt(10)
	v_mfma_f32_32x32x16_bf16 v[82:97], v[230:233], v[154:157], v[82:97]
	ds_read_b64_tr_b16 v[210:211], v214 offset:63488
	ds_read_b64_tr_b16 v[212:213], v215 offset:14336
	s_waitcnt lgkmcnt(9)
	v_mfma_f32_32x32x16_bf16 v[98:113], v[206:209], v[150:153], v[98:113]
	s_waitcnt lgkmcnt(8)
	v_mfma_f32_32x32x16_bf16 v[82:97], v[222:225], v[150:153], v[82:97]
	ds_read_b64_tr_b16 v[206:207], v214 offset:51712
	ds_read_b64_tr_b16 v[208:209], v214 offset:53760
	s_waitcnt lgkmcnt(7)
	v_mfma_f32_32x32x16_bf16 v[98:113], v[218:221], v[158:161], v[98:113]
	s_waitcnt lgkmcnt(6)
	v_mfma_f32_32x32x16_bf16 v[82:97], v[226:229], v[158:161], v[82:97]
	ds_read_b64_tr_b16 v[218:219], v214 offset:55808
	ds_read_b64_tr_b16 v[220:221], v214 offset:57856
	v_mfma_f32_32x32x16_bf16 v[50:65], v[162:165], v[234:237], v[50:65]
	ds_read_b64_tr_b16 v[222:223], v214 offset:59904
	ds_read_b64_tr_b16 v[224:225], v214 offset:61952
	v_mfma_f32_32x32x16_bf16 v[50:65], v[166:169], v[238:241], v[50:65]
	ds_read_b64_tr_b16 v[226:227], v214 offset:64000
	ds_read_b64_tr_b16 v[228:229], v215 offset:14848
	s_waitcnt lgkmcnt(10)
	v_mfma_f32_32x32x16_bf16 v[50:65], v[170:173], v[242:245], v[50:65]
	ds_read_b64_tr_b16 v[230:231], v214 offset:52224
	ds_read_b64_tr_b16 v[232:233], v214 offset:54272
	s_waitcnt lgkmcnt(10)
	v_mfma_f32_32x32x16_bf16 v[50:65], v[174:177], v[210:213], v[50:65]
	ds_read_b64_tr_b16 v[210:211], v214 offset:56320
	ds_read_b64_tr_b16 v[212:213], v214 offset:58368
	s_waitcnt lgkmcnt(10)
	v_mfma_f32_32x32x16_bf16 v[34:49], v[162:165], v[206:209], v[34:49]
	ds_read_b64_tr_b16 v[206:207], v214 offset:60416
	ds_read_b64_tr_b16 v[208:209], v214 offset:62464
	s_waitcnt lgkmcnt(10)
	v_mfma_f32_32x32x16_bf16 v[34:49], v[166:169], v[218:221], v[34:49]
	ds_read_b64_tr_b16 v[218:219], v214 offset:64512
	ds_read_b64_tr_b16 v[220:221], v215 offset:15360
	s_waitcnt lgkmcnt(10)
	v_mfma_f32_32x32x16_bf16 v[34:49], v[170:173], v[222:225], v[34:49]
	ds_read_b64_tr_b16 v[222:223], v214 offset:52736
	ds_read_b64_tr_b16 v[224:225], v214 offset:54784
	s_waitcnt lgkmcnt(10)
	v_mfma_f32_32x32x16_bf16 v[34:49], v[174:177], v[226:229], v[34:49]
	ds_read_b64_tr_b16 v[226:227], v214 offset:56832
	ds_read_b64_tr_b16 v[228:229], v214 offset:58880
	s_waitcnt lgkmcnt(10)
	v_mfma_f32_32x32x16_bf16 v[18:33], v[162:165], v[230:233], v[18:33]
	ds_read_b64_tr_b16 v[230:231], v214 offset:60928
	ds_read_b64_tr_b16 v[232:233], v214 offset:62976
	s_waitcnt lgkmcnt(10)
	v_mfma_f32_32x32x16_bf16 v[18:33], v[166:169], v[210:213], v[18:33]
	ds_read_b64_tr_b16 v[210:211], v214 offset:65024
	ds_read_b64_tr_b16 v[212:213], v215 offset:15872
	s_waitcnt lgkmcnt(10)
	v_mfma_f32_32x32x16_bf16 v[18:33], v[170:173], v[206:209], v[18:33]
	s_waitcnt lgkmcnt(8)
	v_mfma_f32_32x32x16_bf16 v[18:33], v[174:177], v[218:221], v[18:33]
	s_waitcnt lgkmcnt(6)
	v_mfma_f32_32x32x16_bf16 v[2:17], v[162:165], v[222:225], v[2:17]
	s_waitcnt lgkmcnt(4)
	v_mfma_f32_32x32x16_bf16 v[2:17], v[166:169], v[226:229], v[2:17]
	s_waitcnt lgkmcnt(2)
	v_mfma_f32_32x32x16_bf16 v[2:17], v[170:173], v[230:233], v[2:17]
	s_waitcnt lgkmcnt(0)
	v_mfma_f32_32x32x16_bf16 v[2:17], v[174:177], v[210:213], v[2:17]
	s_and_b64 vcc, exec, s[4:5]
	s_cbranch_vccnz .LBB0_872
	s_waitcnt vmcnt(0) lgkmcnt(0)
	s_barrier
	s_cmpk_gt_u32 s53, 0x7d
	s_cbranch_scc1 .LBB0_870
	s_add_u32 s0, s74, s8
	s_addc_u32 s1, s33, s9
	s_add_u32 s0, s0, 0x36020000
	s_addc_u32 s1, s1, 0
	s_add_i32 s55, s55, 0
	v_lshl_add_u64 v[162:163], v[182:183], 1, s[0:1]
	s_add_i32 s62, s55, s54
	s_mov_b32 s63, m0
	s_mov_b32 m0, s62
	s_nop 0
	global_load_lds_dwordx4 v[162:163], off
	s_mov_b32 m0, s63
	v_lshl_add_u64 v[162:163], v[184:185], 1, s[0:1]
	s_add_i32 s62, s55, s71
	s_mov_b32 s63, m0
	s_mov_b32 m0, s62
	s_nop 0
	global_load_lds_dwordx4 v[162:163], off
	s_mov_b32 m0, s63
	v_lshl_add_u64 v[162:163], v[186:187], 1, s[0:1]
	s_add_i32 s55, s55, s70
	s_mov_b32 s0, m0
	s_mov_b32 m0, s55
	s_nop 0
	global_load_lds_dwordx4 v[162:163], off
	s_mov_b32 m0, s0

.LBB0_2806:
	s_bitcmp1_b32 s82, 0
	s_cselect_b32 s86, 0x6400, 0
	s_and_b32 s85, s84, 0x4000
	v_add_u32_e32 v205, s86, v201
	ds_read_b128 v[82:85], v205
	ds_read_b128 v[206:209], v205 offset:32
	ds_read_b128 v[210:213], v205 offset:12800
	ds_read_b128 v[218:221], v205 offset:64
	ds_read_b128 v[222:225], v205 offset:12832
	ds_read_b128 v[226:229], v205 offset:12864
	v_add_u32_e32 v214, s85, v204
	v_add_u32_e32 v215, 0xc800, v214
	s_and_b64 vcc, exec, s[6:7]
	s_cbranch_vccnz .LBB0_2811
	s_cmp_eq_u32 s8, 0x2f40000
	s_cbranch_scc1 .LBB0_2810
	s_add_u32 s0, s33, s8
	s_addc_u32 s1, s78, s9
	s_add_u32 s0, s0, 0x35fc0000
	s_addc_u32 s1, s1, 0
	s_sub_i32 s62, 0, s86
	s_add_i32 s63, s62, 0x6400
	v_lshl_add_u64 v[230:231], v[182:183], 1, s[0:1]
	s_add_i32 s66, s63, s70
	s_mov_b32 s67, m0
	s_mov_b32 m0, s66
	s_nop 0
	global_load_lds_dwordx4 v[230:231], off
	s_mov_b32 m0, s67
	v_lshl_add_u64 v[230:231], v[184:185], 1, s[0:1]
	s_add_i32 s66, s63, s71
	s_mov_b32 s67, m0
	s_mov_b32 m0, s66
	s_nop 0
	global_load_lds_dwordx4 v[230:231], off
	s_mov_b32 m0, s67
	v_lshl_add_u64 v[230:231], v[186:187], 1, s[0:1]
	s_add_i32 s63, s63, s83
	s_mov_b32 s66, m0
	s_mov_b32 m0, s63
	s_nop 0
	global_load_lds_dwordx4 v[230:231], off
	s_mov_b32 m0, s66
	s_and_b64 vcc, exec, s[2:3]
	s_cbranch_vccnz .LBB0_2810
	s_add_i32 s62, s62, 0xc400
	v_lshl_add_u64 v[230:231], v[188:189], 1, s[0:1]
	s_mov_b32 s0, m0
	s_mov_b32 m0, s62
	s_nop 0
	global_load_lds_dwordx4 v[230:231], off
	s_mov_b32 m0, s0
.LBB0_2810:
	s_sub_i32 s0, 0, s85
	s_add_i32 s0, s0, 0x10800
	v_lshl_add_u64 v[230:231], v[190:191], 1, s[76:77]
	s_add_i32 s1, s0, s70
	s_mov_b32 s62, m0
	s_mov_b32 m0, s1
	s_nop 0
	global_load_lds_dwordx4 v[230:231], off
	s_mov_b32 m0, s62
	v_lshl_add_u64 v[230:231], v[192:193], 1, s[76:77]
	s_add_i32 s0, s0, s71
	s_mov_b32 s1, m0
	s_mov_b32 m0, s0
	s_nop 0
	global_load_lds_dwordx4 v[230:231], off
	s_mov_b32 m0, s1
.LBB0_2811:
	s_waitcnt lgkmcnt(5)
	v_mfma_f32_32x32x16_bf16 v[98:113], v[82:85], v[114:117], v[66:81]
	s_waitcnt lgkmcnt(3)
	v_mfma_f32_32x32x16_bf16 v[82:97], v[210:213], v[114:117], v[66:81]
	ds_read_b128 v[210:213], v205 offset:96
	ds_read_b128 v[230:233], v205 offset:12896
	v_mfma_f32_32x32x16_bf16 v[98:113], v[206:209], v[118:121], v[98:113]
	s_waitcnt lgkmcnt(3)
	v_mfma_f32_32x32x16_bf16 v[82:97], v[222:225], v[118:121], v[82:97]
	ds_read_b128 v[206:209], v205 offset:128
	ds_read_b128 v[222:225], v205 offset:12928
	v_mfma_f32_32x32x16_bf16 v[98:113], v[218:221], v[122:125], v[98:113]
	s_waitcnt lgkmcnt(4)
	v_mfma_f32_32x32x16_bf16 v[82:97], v[226:229], v[122:125], v[82:97]
	ds_read_b128 v[218:221], v205 offset:160
	ds_read_b128 v[226:229], v205 offset:12960
	s_waitcnt lgkmcnt(5)
	v_mfma_f32_32x32x16_bf16 v[98:113], v[210:213], v[126:129], v[98:113]
	s_waitcnt lgkmcnt(4)
	v_mfma_f32_32x32x16_bf16 v[82:97], v[230:233], v[126:129], v[82:97]
	ds_read_b128 v[210:213], v205 offset:192
	ds_read_b128 v[230:233], v205 offset:12992
	s_waitcnt lgkmcnt(5)
	v_mfma_f32_32x32x16_bf16 v[98:113], v[206:209], v[130:133], v[98:113]
	s_waitcnt lgkmcnt(4)
	v_mfma_f32_32x32x16_bf16 v[82:97], v[222:225], v[130:133], v[82:97]
	ds_read_b128 v[206:209], v205 offset:224
	ds_read_b128 v[222:225], v205 offset:13024
	s_waitcnt lgkmcnt(5)
	v_mfma_f32_32x32x16_bf16 v[98:113], v[218:221], v[134:137], v[98:113]
	s_waitcnt lgkmcnt(4)
	v_mfma_f32_32x32x16_bf16 v[82:97], v[226:229], v[134:137], v[82:97]
	ds_read_b128 v[218:221], v205 offset:256
	ds_read_b128 v[226:229], v205 offset:13056
	s_waitcnt lgkmcnt(5)
	v_mfma_f32_32x32x16_bf16 v[98:113], v[210:213], v[138:141], v[98:113]
	s_waitcnt lgkmcnt(4)
	v_mfma_f32_32x32x16_bf16 v[82:97], v[230:233], v[138:141], v[82:97]
	ds_read_b128 v[210:213], v205 offset:288
	ds_read_b128 v[230:233], v205 offset:13088
	ds_read_b64_tr_b16 v[234:235], v214 offset:51200
	ds_read_b64_tr_b16 v[236:237], v214 offset:53248
	s_waitcnt lgkmcnt(7)
	v_mfma_f32_32x32x16_bf16 v[98:113], v[206:209], v[142:145], v[98:113]
	s_waitcnt lgkmcnt(6)
	v_mfma_f32_32x32x16_bf16 v[82:97], v[222:225], v[142:145], v[82:97]
	ds_read_b128 v[206:209], v205 offset:320
	ds_read_b128 v[222:225], v205 offset:13120
	ds_read_b64_tr_b16 v[238:239], v214 offset:55296
	ds_read_b64_tr_b16 v[240:241], v214 offset:57344
	s_waitcnt lgkmcnt(9)
	v_mfma_f32_32x32x16_bf16 v[98:113], v[218:221], v[146:149], v[98:113]
	s_waitcnt lgkmcnt(8)
	v_mfma_f32_32x32x16_bf16 v[82:97], v[226:229], v[146:149], v[82:97]
	ds_read_b128 v[218:221], v205 offset:352
	ds_read_b128 v[226:229], v205 offset:13152
	ds_read_b64_tr_b16 v[242:243], v214 offset:59392
	ds_read_b64_tr_b16 v[244:245], v214 offset:61440
	s_waitcnt lgkmcnt(11)
	v_mfma_f32_32x32x16_bf16 v[98:113], v[210:213], v[154:157], v[98:113]
	s_waitcnt lgkmcnt(10)
	v_mfma_f32_32x32x16_bf16 v[82:97], v[230:233], v[154:157], v[82:97]
	ds_read_b64_tr_b16 v[210:211], v214 offset:63488
	ds_read_b64_tr_b16 v[212:213], v215 offset:14336
	s_waitcnt lgkmcnt(9)
	v_mfma_f32_32x32x16_bf16 v[98:113], v[206:209], v[150:153], v[98:113]
	s_waitcnt lgkmcnt(8)
	v_mfma_f32_32x32x16_bf16 v[82:97], v[222:225], v[150:153], v[82:97]
	ds_read_b64_tr_b16 v[206:207], v214 offset:51712
	ds_read_b64_tr_b16 v[208:209], v214 offset:53760
	s_waitcnt lgkmcnt(7)
	v_mfma_f32_32x32x16_bf16 v[98:113], v[218:221], v[158:161], v[98:113]
	s_waitcnt lgkmcnt(6)
	v_mfma_f32_32x32x16_bf16 v[82:97], v[226:229], v[158:161], v[82:97]
	ds_read_b64_tr_b16 v[218:219], v214 offset:55808
	ds_read_b64_tr_b16 v[220:221], v214 offset:57856
	v_mfma_f32_32x32x16_bf16 v[50:65], v[162:165], v[234:237], v[50:65]
	ds_read_b64_tr_b16 v[222:223], v214 offset:59904
	ds_read_b64_tr_b16 v[224:225], v214 offset:61952
	v_mfma_f32_32x32x16_bf16 v[50:65], v[166:169], v[238:241], v[50:65]
	ds_read_b64_tr_b16 v[226:227], v214 offset:64000
	ds_read_b64_tr_b16 v[228:229], v215 offset:14848
	s_waitcnt lgkmcnt(10)
	v_mfma_f32_32x32x16_bf16 v[50:65], v[170:173], v[242:245], v[50:65]
	ds_read_b64_tr_b16 v[230:231], v214 offset:52224
	ds_read_b64_tr_b16 v[232:233], v214 offset:54272
	s_waitcnt lgkmcnt(10)
	v_mfma_f32_32x32x16_bf16 v[50:65], v[174:177], v[210:213], v[50:65]
	ds_read_b64_tr_b16 v[210:211], v214 offset:56320
	ds_read_b64_tr_b16 v[212:213], v214 offset:58368
	s_waitcnt lgkmcnt(10)
	v_mfma_f32_32x32x16_bf16 v[34:49], v[162:165], v[206:209], v[34:49]
	ds_read_b64_tr_b16 v[206:207], v214 offset:60416
	ds_read_b64_tr_b16 v[208:209], v214 offset:62464
	s_waitcnt lgkmcnt(10)
	v_mfma_f32_32x32x16_bf16 v[34:49], v[166:169], v[218:221], v[34:49]
	ds_read_b64_tr_b16 v[218:219], v214 offset:64512
	ds_read_b64_tr_b16 v[220:221], v215 offset:15360
	s_waitcnt lgkmcnt(10)
	v_mfma_f32_32x32x16_bf16 v[34:49], v[170:173], v[222:225], v[34:49]
	ds_read_b64_tr_b16 v[222:223], v214 offset:52736
	ds_read_b64_tr_b16 v[224:225], v214 offset:54784
	s_waitcnt lgkmcnt(10)
	v_mfma_f32_32x32x16_bf16 v[34:49], v[174:177], v[226:229], v[34:49]
	ds_read_b64_tr_b16 v[226:227], v214 offset:56832
	ds_read_b64_tr_b16 v[228:229], v214 offset:58880
	s_waitcnt lgkmcnt(10)
	v_mfma_f32_32x32x16_bf16 v[18:33], v[162:165], v[230:233], v[18:33]
	ds_read_b64_tr_b16 v[230:231], v214 offset:60928
	ds_read_b64_tr_b16 v[232:233], v214 offset:62976
	s_waitcnt lgkmcnt(10)
	v_mfma_f32_32x32x16_bf16 v[18:33], v[166:169], v[210:213], v[18:33]
	ds_read_b64_tr_b16 v[210:211], v214 offset:65024
	ds_read_b64_tr_b16 v[212:213], v215 offset:15872
	s_waitcnt lgkmcnt(10)
	v_mfma_f32_32x32x16_bf16 v[18:33], v[170:173], v[206:209], v[18:33]
	s_waitcnt lgkmcnt(8)
	v_mfma_f32_32x32x16_bf16 v[18:33], v[174:177], v[218:221], v[18:33]
	s_waitcnt lgkmcnt(6)
	v_mfma_f32_32x32x16_bf16 v[2:17], v[162:165], v[222:225], v[2:17]
	s_waitcnt lgkmcnt(4)
	v_mfma_f32_32x32x16_bf16 v[2:17], v[166:169], v[226:229], v[2:17]
	s_waitcnt lgkmcnt(2)
	v_mfma_f32_32x32x16_bf16 v[2:17], v[170:173], v[230:233], v[2:17]
	s_waitcnt lgkmcnt(0)
	v_mfma_f32_32x32x16_bf16 v[2:17], v[174:177], v[210:213], v[2:17]
	s_and_b64 vcc, exec, s[4:5]
	s_cbranch_vccnz .LBB0_2816
	s_waitcnt vmcnt(0) lgkmcnt(0)
	s_barrier
	s_cmpk_gt_u32 s82, 0x7d
	s_cbranch_scc1 .LBB0_2814
	s_add_u32 s0, s33, s8
	s_addc_u32 s1, s78, s9
	s_add_u32 s0, s0, 0x36020000
	s_addc_u32 s1, s1, 0
	s_add_i32 s62, s86, 0
	v_lshl_add_u64 v[162:163], v[182:183], 1, s[0:1]
	s_add_i32 s63, s62, s70
	s_mov_b32 s66, m0
	s_mov_b32 m0, s63
	s_nop 0
	global_load_lds_dwordx4 v[162:163], off
	s_mov_b32 m0, s66
	v_lshl_add_u64 v[162:163], v[184:185], 1, s[0:1]
	s_add_i32 s63, s62, s71
	s_mov_b32 s66, m0
	s_mov_b32 m0, s63
	s_nop 0
	global_load_lds_dwordx4 v[162:163], off
	s_mov_b32 m0, s66
	v_lshl_add_u64 v[162:163], v[186:187], 1, s[0:1]
	s_add_i32 s62, s62, s83
	s_mov_b32 s0, m0
	s_mov_b32 m0, s62
	s_nop 0
	global_load_lds_dwordx4 v[162:163], off
	s_mov_b32 m0, s0
